# xattn: PV loop pipelined ds_read_b64 + all-at-once K/V staging loads
# speedup vs baseline: 1.0052x; 1.0052x over previous
.LBB0_1949:
	s_mul_hi_i32 s0, s69, 0x2aaaaaab
	s_lshr_b32 s1, s0, 31
	s_ashr_i32 s0, s0, 6
	s_add_i32 s0, s0, s1
	s_mul_i32 s1, s0, 0x180
	s_sub_i32 s10, s69, s1
	s_lshl_b32 s1, s10, 7
	s_add_i32 s12, s1, 0xffffc000
	s_lshr_b32 s12, s12, 12
	s_ashr_i32 s11, s10, 6
	s_add_i32 s12, s12, 2
	s_cmpk_lt_i32 s10, 0x80
	s_cselect_b32 s12, s11, s12
	s_lshl_b32 s14, s0, 8
	s_ashr_i32 s13, s12, 31
	s_ashr_i32 s15, s14, 31
	s_lshl_b64 s[16:17], s[12:13], 19
	s_lshl_b64 s[10:11], s[14:15], 1
	s_add_u32 s16, s16, s10
	s_addc_u32 s17, s17, s11
	v_lshl_add_u64 v[208:209], v[58:59], 0, s[16:17]
	v_lshl_add_u64 v[210:211], v[60:61], 0, s[16:17]
	v_lshl_add_u64 v[212:213], v[62:63], 0, s[16:17]
	v_add_co_u32_e32 v212, vcc, 0x19000000, v212
	s_mov_b32 s17, 0
	s_mov_b32 s16, 0x10000
	v_addc_co_u32_e32 v213, vcc, 0, v213, vcc
	global_load_dwordx4 v[142:145], v[212:213], off
	global_load_dwordx4 v[146:149], v[210:211], off
	v_lshl_add_u64 v[214:215], v[212:213], 0, s[16:17]
	global_load_dwordx4 v[150:153], v[214:215], off
	global_load_dwordx4 v[154:157], v[208:209], off
	s_mov_b32 s16, 0x20000
	v_lshl_add_u64 v[214:215], v[212:213], 0, s[16:17]
	global_load_dwordx4 v[158:161], v[214:215], off
	v_lshl_add_u64 v[216:217], v[210:211], 0, s[16:17]
	global_load_dwordx4 v[162:165], v[216:217], off
	v_lshl_add_u64 v[218:219], v[208:209], 0, s[16:17]
	global_load_dwordx4 v[170:173], v[218:219], off
	s_mov_b32 s16, 0x30000
	v_lshl_add_u64 v[214:215], v[212:213], 0, s[16:17]
	global_load_dwordx4 v[166:169], v[214:215], off
	s_mov_b32 s16, 0x40000
	v_lshl_add_u64 v[214:215], v[212:213], 0, s[16:17]
	global_load_dwordx4 v[174:177], v[214:215], off
	v_lshl_add_u64 v[216:217], v[210:211], 0, s[16:17]
	global_load_dwordx4 v[178:181], v[216:217], off
	v_lshl_add_u64 v[218:219], v[208:209], 0, s[16:17]
	global_load_dwordx4 v[188:191], v[218:219], off
	s_mov_b32 s16, 0x50000
	v_lshl_add_u64 v[214:215], v[212:213], 0, s[16:17]
	global_load_dwordx4 v[184:187], v[214:215], off
	s_mov_b32 s16, 0x60000
	v_lshl_add_u64 v[214:215], v[212:213], 0, s[16:17]
	global_load_dwordx4 v[192:195], v[214:215], off
	v_lshl_add_u64 v[216:217], v[210:211], 0, s[16:17]
	global_load_dwordx4 v[196:199], v[216:217], off
	v_lshl_add_u64 v[218:219], v[208:209], 0, s[16:17]
	global_load_dwordx4 v[204:207], v[218:219], off
	s_mov_b32 s16, 0x70000
	v_lshl_add_u64 v[214:215], v[212:213], 0, s[16:17]
	global_load_dwordx4 v[200:203], v[214:215], off
	v_add_u32_e32 v0, s1, v82
	v_ashrrev_i32_e32 v1, 31, v0
	v_lshlrev_b64 v[72:73], 11, v[0:1]
	v_lshl_add_u64 v[2:3], s[4:5], 0, v[72:73]
	v_lshl_add_u64 v[2:3], s[14:15], 1, v[2:3]
	v_lshl_add_u64 v[2:3], v[2:3], 0, v[52:53]
	global_load_dwordx4 v[24:27], v[2:3], off
	global_load_dwordx4 v[16:19], v[2:3], off offset:64
	global_load_dwordx4 v[12:15], v[2:3], off offset:128
	s_ashr_i32 s1, s0, 31
	v_lshl_add_u64 v[0:1], v[0:1], 4, s[6:7]
	v_lshl_add_u64 v[0:1], s[0:1], 2, v[0:1]
	global_load_dword v74, v[0:1], off
	global_load_dword v75, v[54:55], off
	global_load_dword v183, v[54:55], off offset:256
	global_load_dword v228, v[54:55], off offset:512
	global_load_dword v229, v[54:55], off offset:768
	global_load_dword v230, v[56:57], off
	global_load_dword v231, v[56:57], off offset:256
	global_load_dword v232, v[56:57], off offset:512
	global_load_dword v233, v[56:57], off offset:768
	global_load_dwordx4 v[28:31], v[2:3], off offset:192
	global_load_dwordx4 v[20:23], v[2:3], off offset:256
	global_load_dwordx4 v[8:11], v[2:3], off offset:320
	global_load_dwordx4 v[4:7], v[2:3], off offset:384
	s_nop 0
	global_load_dwordx4 v[0:3], v[2:3], off offset:448
	v_mov_b32_e32 v220, v134
	v_mov_b32_e32 v221, v133
	v_mov_b32_e32 v222, v132
	s_waitcnt vmcnt(29)
	ds_write_b128 v220, v[142:145]
	ds_write_b128 v221, v[146:149]
	ds_write_b128 v220, v[150:153] offset:16896
	ds_write_b128 v222, v[154:157]
	v_add_u32_e32 v220, 0x8400, v220
	v_add_u32_e32 v221, 0x8400, v221
	v_add_u32_e32 v222, 0x8400, v222
	s_waitcnt vmcnt(25)
	ds_write_b128 v220, v[158:161]
	ds_write_b128 v221, v[162:165]
	ds_write_b128 v220, v[166:169] offset:16896
	ds_write_b128 v222, v[170:173]
	v_add_u32_e32 v220, 0x8400, v220
	v_add_u32_e32 v221, 0x8400, v221
	v_add_u32_e32 v222, 0x8400, v222
	s_waitcnt vmcnt(21)
	ds_write_b128 v220, v[174:177]
	ds_write_b128 v221, v[178:181]
	ds_write_b128 v220, v[184:187] offset:16896
	ds_write_b128 v222, v[188:191]
	v_add_u32_e32 v220, 0x8400, v220
	v_add_u32_e32 v221, 0x8400, v221
	v_add_u32_e32 v222, 0x8400, v222
	s_waitcnt vmcnt(17)
	ds_write_b128 v220, v[192:195]
	ds_write_b128 v221, v[196:199]
	ds_write_b128 v220, v[200:203] offset:16896
	ds_write_b128 v222, v[204:207]
	s_waitcnt lgkmcnt(0)
	s_waitcnt lgkmcnt(0)
	s_barrier
	ds_read_b128 v[32:35], v83
	ds_read_b128 v[36:39], v83 offset:64
	ds_read_b128 v[40:43], v83 offset:128
	ds_read_b128 v[44:47], v83 offset:192
	ds_read_b128 v[48:51], v83 offset:256
	ds_read_b128 v[142:145], v83 offset:320
	ds_read_b128 v[146:149], v83 offset:384
	ds_read_b128 v[150:153], v83 offset:448
	ds_read_b128 v[154:157], v83 offset:8448
	ds_read_b128 v[158:161], v83 offset:8512
	ds_read_b128 v[162:165], v83 offset:8576
	ds_read_b128 v[166:169], v83 offset:8640
	ds_read_b128 v[170:173], v83 offset:8704
	ds_read_b128 v[174:177], v83 offset:8768
	ds_read_b128 v[178:181], v83 offset:8832
	ds_read_b128 v[184:187], v83 offset:8896
	ds_read_b128 v[188:191], v83 offset:16896
	ds_read_b128 v[192:195], v83 offset:16960
	ds_read_b128 v[196:199], v83 offset:17024
	ds_read_b128 v[200:203], v83 offset:17088
	ds_read_b128 v[204:207], v83 offset:17152
	ds_read_b128 v[208:211], v83 offset:17216
	ds_read_b128 v[212:215], v83 offset:17280
	ds_read_b128 v[216:219], v83 offset:17344
	ds_read_b128 v[220:223], v138
	ds_read_b128 v[224:227], v138 offset:64
	s_mul_hi_i32 s14, s0, 0x140000
	s_mul_i32 s15, s0, 0x140000
	s_lshl_b32 s12, s12, 8
	s_ashr_i32 s13, s12, 31
	s_waitcnt vmcnt(16) lgkmcnt(14)
	v_mfma_f32_16x16x32_bf16 v[32:35], v[32:35], v[24:27], 0
	s_waitcnt vmcnt(8)
	v_mul_f32_e32 v75, v75, v230
	v_fmamk_f32 v74, v74, 0x3b800000, v136
	v_cmp_gt_f32_e32 vcc, s18, v74
	v_mfma_f32_16x16x32_bf16 v[32:35], v[36:39], v[16:19], v[32:35]
	v_mfma_f32_16x16x32_bf16 v[154:157], v[154:157], v[24:27], 0
	s_waitcnt lgkmcnt(9)
	v_mfma_f32_16x16x32_bf16 v[188:191], v[188:191], v[24:27], 0
	v_mfma_f32_16x16x32_bf16 v[32:35], v[40:43], v[12:15], v[32:35]
	v_mfma_f32_16x16x32_bf16 v[36:39], v[158:161], v[16:19], v[154:157]
	s_waitcnt lgkmcnt(8)
	v_mfma_f32_16x16x32_bf16 v[154:157], v[192:195], v[16:19], v[188:191]
	s_waitcnt vmcnt(4)
	v_mfma_f32_16x16x32_bf16 v[32:35], v[44:47], v[28:31], v[32:35]
	v_mfma_f32_16x16x32_bf16 v[36:39], v[162:165], v[12:15], v[36:39]
	s_waitcnt lgkmcnt(7)
	v_mfma_f32_16x16x32_bf16 v[40:43], v[196:199], v[12:15], v[154:157]
	s_nop 2
	ds_read_b128 v[154:157], v138 offset:128
	ds_read_b128 v[162:165], v138 offset:192
	s_waitcnt vmcnt(3)
	v_mfma_f32_16x16x32_bf16 v[32:35], v[48:51], v[20:23], v[32:35]
	v_mfma_f32_16x16x32_bf16 v[36:39], v[166:169], v[28:31], v[36:39]
	s_waitcnt lgkmcnt(8)
	v_mfma_f32_16x16x32_bf16 v[40:43], v[200:203], v[28:31], v[40:43]
	s_waitcnt vmcnt(2)
	v_mfma_f32_16x16x32_bf16 v[32:35], v[142:145], v[8:11], v[32:35]
	s_waitcnt lgkmcnt(3)
	v_mfma_f32_16x16x32_bf16 v[220:223], v[220:223], v[24:27], 0
	v_mfma_f32_16x16x32_bf16 v[36:39], v[170:173], v[20:23], v[36:39]
	v_mfma_f32_16x16x32_bf16 v[40:43], v[204:207], v[20:23], v[40:43]
	s_waitcnt vmcnt(1)
	v_mfma_f32_16x16x32_bf16 v[32:35], v[146:149], v[4:7], v[32:35]
	s_waitcnt lgkmcnt(2)
	v_mfma_f32_16x16x32_bf16 v[158:161], v[224:227], v[16:19], v[220:223]
	v_mfma_f32_16x16x32_bf16 v[36:39], v[174:177], v[8:11], v[36:39]
	v_mfma_f32_16x16x32_bf16 v[40:43], v[208:211], v[8:11], v[40:43]
	s_waitcnt vmcnt(0)
	v_mfma_f32_16x16x32_bf16 v[142:145], v[150:153], v[0:3], v[32:35]
	s_nop 2
	ds_read_b128 v[32:35], v138 offset:256
	s_waitcnt lgkmcnt(2)
	v_mfma_f32_16x16x32_bf16 v[154:157], v[154:157], v[12:15], v[158:161]
	v_mfma_f32_16x16x32_bf16 v[36:39], v[178:181], v[4:7], v[36:39]
	v_mfma_f32_16x16x32_bf16 v[48:51], v[212:215], v[4:7], v[40:43]
	s_waitcnt lgkmcnt(1)
	v_mfma_f32_16x16x32_bf16 v[44:47], v[162:165], v[28:31], v[154:157]
	v_mul_f32_e32 v163, 0x4f800000, v74
	v_cndmask_b32_e32 v74, v74, v163, vcc
	v_sqrt_f32_e32 v163, v74
	v_mfma_f32_16x16x32_bf16 v[40:43], v[184:187], v[0:3], v[36:39]
	v_mul_f32_e32 v154, v183, v231
	v_max3_f32 v75, |v75|, 0, |v154|
	v_mul_f32_e32 v154, v228, v232
	v_mfma_f32_16x16x32_bf16 v[36:39], v[216:219], v[0:3], v[48:51]
	s_nop 2
	ds_read_b128 v[48:51], v138 offset:320
	s_waitcnt lgkmcnt(1)
	v_mfma_f32_16x16x32_bf16 v[32:35], v[32:35], v[20:23], v[44:47]
	s_nop 2
	ds_read_b128 v[44:47], v138 offset:384
	s_waitcnt lgkmcnt(1)
	v_mfma_f32_16x16x32_bf16 v[32:35], v[48:51], v[8:11], v[32:35]
	ds_read_b128 v[48:51], v138 offset:448
	s_waitcnt lgkmcnt(1)
	v_mfma_f32_16x16x32_bf16 v[32:35], v[44:47], v[4:7], v[32:35]
	ds_read_b128 v[44:47], v83 offset:33792
	s_waitcnt lgkmcnt(1)
	v_mfma_f32_16x16x32_bf16 v[32:35], v[48:51], v[0:3], v[32:35]
	ds_read_b128 v[48:51], v83 offset:33856
	ds_read_b128 v[146:149], v83 offset:33920
	ds_read_b128 v[150:153], v83 offset:33984
	s_waitcnt lgkmcnt(3)
	v_mfma_f32_16x16x32_bf16 v[44:47], v[44:47], v[24:27], 0
	s_waitcnt lgkmcnt(2)
	v_mfma_f32_16x16x32_bf16 v[44:47], v[48:51], v[16:19], v[44:47]
	ds_read_b128 v[48:51], v83 offset:34048
	s_waitcnt lgkmcnt(2)
	v_mfma_f32_16x16x32_bf16 v[44:47], v[146:149], v[12:15], v[44:47]
	v_mul_f32_e32 v146, v229, v233
	v_max3_f32 v75, v75, |v154|, |v146|
	ds_read_b128 v[146:149], v83 offset:34112
	s_waitcnt lgkmcnt(2)
	v_mfma_f32_16x16x32_bf16 v[44:47], v[150:153], v[28:31], v[44:47]
	ds_bpermute_b32 v154, v76, v75
	ds_read_b128 v[150:153], v83 offset:34176
	s_waitcnt lgkmcnt(3)
	v_mfma_f32_16x16x32_bf16 v[44:47], v[48:51], v[20:23], v[44:47]
	s_waitcnt lgkmcnt(1)
	v_max_f32_e32 v48, v154, v154
	v_max_f32_e32 v75, v75, v48
	ds_bpermute_b32 v154, v77, v75
	ds_read_b128 v[48:51], v83 offset:34240
	v_mfma_f32_16x16x32_bf16 v[44:47], v[146:149], v[8:11], v[44:47]
	ds_read_b128 v[146:149], v83 offset:42240
	s_waitcnt lgkmcnt(3)
	v_mfma_f32_16x16x32_bf16 v[44:47], v[150:153], v[4:7], v[44:47]
	s_waitcnt lgkmcnt(2)
	v_max_f32_e32 v150, v154, v154
	v_max_f32_e32 v75, v75, v150
	ds_read_b128 v[150:153], v83 offset:42304
	ds_bpermute_b32 v154, v78, v75
	s_waitcnt lgkmcnt(3)
	v_mfma_f32_16x16x32_bf16 v[44:47], v[48:51], v[0:3], v[44:47]
	ds_read_b128 v[48:51], v83 offset:42368
	s_waitcnt lgkmcnt(1)
	v_max_f32_e32 v154, v154, v154
	v_mfma_f32_16x16x32_bf16 v[146:149], v[146:149], v[24:27], 0
	v_max_f32_e32 v75, v75, v154
	ds_read_b128 v[154:157], v83 offset:42432
	ds_bpermute_b32 v158, v79, v75
	v_mfma_f32_16x16x32_bf16 v[146:149], v[150:153], v[16:19], v[146:149]
	ds_read_b128 v[150:153], v83 offset:42496
	s_waitcnt lgkmcnt(3)
	v_mfma_f32_16x16x32_bf16 v[48:51], v[48:51], v[12:15], v[146:149]
	s_waitcnt lgkmcnt(2)
	v_mfma_f32_16x16x32_bf16 v[48:51], v[154:157], v[28:31], v[48:51]
	s_waitcnt lgkmcnt(1)
	s_nop 1
	v_max_f32_e32 v146, v158, v158
	v_max_f32_e32 v75, v75, v146
	ds_read_b128 v[146:149], v83 offset:42560
	ds_read_b128 v[154:157], v83 offset:42624
	s_waitcnt lgkmcnt(2)
	v_mfma_f32_16x16x32_bf16 v[48:51], v[150:153], v[20:23], v[48:51]
	ds_read_b128 v[150:153], v83 offset:42688
	ds_bpermute_b32 v158, v80, v75
	s_waitcnt lgkmcnt(3)
	v_mfma_f32_16x16x32_bf16 v[48:51], v[146:149], v[8:11], v[48:51]
	ds_read_b128 v[146:149], v83 offset:50688
	s_waitcnt lgkmcnt(1)
	v_max_f32_e32 v158, v158, v158
	v_max_f32_e32 v75, v75, v158
	v_mfma_f32_16x16x32_bf16 v[48:51], v[154:157], v[4:7], v[48:51]
	ds_read_b128 v[154:157], v83 offset:50752
	ds_bpermute_b32 v158, v81, v75
	s_waitcnt lgkmcnt(0)
	v_max_f32_e32 v162, v158, v158
	v_mfma_f32_16x16x32_bf16 v[48:51], v[150:153], v[0:3], v[48:51]
	ds_read_b128 v[150:153], v83 offset:50816
	ds_read_b128 v[158:161], v83 offset:50880
	v_max_f32_e32 v75, v75, v162
	v_mfma_f32_16x16x32_bf16 v[146:149], v[146:149], v[24:27], 0
	v_add_u32_e32 v162, -1, v163
	v_fma_f32 v164, -v162, v163, v74
	v_cmp_ge_f32_e64 s[0:1], 0, v164
	v_mfma_f32_16x16x32_bf16 v[146:149], v[154:157], v[16:19], v[146:149]
	ds_read_b128 v[154:157], v83 offset:50944
	v_add_u32_e32 v164, 1, v163
	v_cndmask_b32_e64 v162, v163, v162, s[0:1]
	s_waitcnt lgkmcnt(2)
	v_mfma_f32_16x16x32_bf16 v[146:149], v[150:153], v[12:15], v[146:149]
	ds_read_b128 v[150:153], v83 offset:51008
	v_fma_f32 v163, -v164, v163, v74
	v_cmp_lt_f32_e64 s[0:1], 0, v163
	s_waitcnt lgkmcnt(2)
	v_mfma_f32_16x16x32_bf16 v[146:149], v[158:161], v[28:31], v[146:149]
	ds_read_b128 v[158:161], v83 offset:51072
	v_cndmask_b32_e64 v162, v162, v164, s[0:1]
	v_mul_f32_e32 v75, 0x41800000, v75
	s_waitcnt lgkmcnt(2)
	v_mfma_f32_16x16x32_bf16 v[146:149], v[154:157], v[20:23], v[146:149]
	ds_read_b128 v[154:157], v83 offset:51136
	s_waitcnt lgkmcnt(2)
	v_mfma_f32_16x16x32_bf16 v[146:149], v[150:153], v[8:11], v[146:149]
	ds_read_b128 v[150:153], v139
	s_waitcnt lgkmcnt(2)
	v_mfma_f32_16x16x32_bf16 v[146:149], v[158:161], v[4:7], v[146:149]
	ds_read_b128 v[158:161], v139 offset:64
	s_waitcnt lgkmcnt(2)
	v_mfma_f32_16x16x32_bf16 v[146:149], v[154:157], v[0:3], v[146:149]
	v_mul_f32_e32 v154, 0x37800000, v162
	v_cndmask_b32_e32 v162, v162, v154, vcc
	ds_read_b128 v[154:157], v139 offset:128
	s_waitcnt lgkmcnt(2)
	v_mfma_f32_16x16x32_bf16 v[150:153], v[150:153], v[24:27], 0
	v_cmp_class_f32_e32 vcc, v74, v137
	s_nop 1
	v_cndmask_b32_e32 v74, v162, v74, vcc
	ds_read_b128 v[162:165], v139 offset:192
	s_waitcnt lgkmcnt(2)
	v_mfma_f32_16x16x32_bf16 v[150:153], v[158:161], v[16:19], v[150:153]
	ds_read_b128 v[158:161], v139 offset:256
	v_div_scale_f32 v166, s[0:1], v74, v74, 1.0
	s_waitcnt lgkmcnt(2)
	v_mfma_f32_16x16x32_bf16 v[150:153], v[154:157], v[12:15], v[150:153]
	v_rcp_f32_e32 v167, v166
	ds_read_b128 v[154:157], v139 offset:320
	v_div_scale_f32 v168, vcc, 1.0, v74, 1.0
	s_waitcnt lgkmcnt(2)
	v_mfma_f32_16x16x32_bf16 v[150:153], v[162:165], v[28:31], v[150:153]
	v_fma_f32 v162, -v166, v167, 1.0
	v_fmac_f32_e32 v167, v162, v167
	ds_read_b128 v[162:165], v139 offset:384
	s_waitcnt lgkmcnt(2)
	v_mfma_f32_16x16x32_bf16 v[150:153], v[158:161], v[20:23], v[150:153]
	ds_read_b128 v[158:161], v139 offset:448
	v_mul_f32_e32 v169, v168, v167
	s_waitcnt lgkmcnt(2)
	v_mfma_f32_16x16x32_bf16 v[150:153], v[154:157], v[8:11], v[150:153]
	ds_read_b128 v[154:157], v84
	v_fma_f32 v170, -v166, v169, v168
	v_fmac_f32_e32 v169, v170, v167
	s_waitcnt lgkmcnt(2)
	v_mfma_f32_16x16x32_bf16 v[150:153], v[162:165], v[4:7], v[150:153]
	ds_read_b128 v[162:165], v85
	v_fma_f32 v166, -v166, v169, v168
	s_lshl_b64 s[0:1], s[12:13], 1
	s_waitcnt lgkmcnt(2)
	v_mfma_f32_16x16x32_bf16 v[150:153], v[158:161], v[0:3], v[150:153]
	v_div_fmas_f32 v158, v166, v167, v169
	v_div_fixup_f32 v74, v158, v74, 1.0
	ds_read_b128 v[158:161], v86
	ds_read_b128 v[166:169], v87
	s_waitcnt lgkmcnt(3)
	v_mfma_f32_16x16x32_bf16 v[154:157], v[154:157], v[24:27], 0
	v_mul_f32_e64 v74, v74, s8
	v_mul_f32_e64 v75, v75, s9
	s_add_u32 s0, s15, s0
	v_fma_f32 v142, v74, v142, -v75
	s_waitcnt lgkmcnt(2)
	v_mfma_f32_16x16x32_bf16 v[154:157], v[162:165], v[16:19], v[154:157]
	ds_read_b128 v[162:165], v88
	v_fma_f32 v143, v74, v143, -v75
	v_fma_f32 v144, v74, v144, -v75
	s_waitcnt lgkmcnt(2)
	v_mfma_f32_16x16x32_bf16 v[154:157], v[158:161], v[12:15], v[154:157]
	ds_read_b128 v[158:161], v89
	v_fma_f32 v145, v74, v145, -v75
	v_fma_f32 v40, v74, v40, -v75
	s_waitcnt lgkmcnt(2)
	v_mfma_f32_16x16x32_bf16 v[154:157], v[166:169], v[28:31], v[154:157]
	ds_read_b128 v[166:169], v90
	v_fma_f32 v41, v74, v41, -v75
	v_fma_f32 v42, v74, v42, -v75
	s_waitcnt lgkmcnt(2)
	v_mfma_f32_16x16x32_bf16 v[154:157], v[162:165], v[20:23], v[154:157]
	ds_read_b128 v[162:165], v91
	ds_read_b128 v[170:173], v95
	s_waitcnt lgkmcnt(3)
	v_mfma_f32_16x16x32_bf16 v[154:157], v[158:161], v[8:11], v[154:157]
	ds_read_b128 v[158:161], v92
	v_fma_f32 v43, v74, v43, -v75
	v_fma_f32 v36, v74, v36, -v75
	s_waitcnt lgkmcnt(3)
	v_mfma_f32_16x16x32_bf16 v[154:157], v[166:169], v[4:7], v[154:157]
	ds_read_b128 v[166:169], v93
	v_fma_f32 v37, v74, v37, -v75
	v_fma_f32 v38, v74, v38, -v75
	s_waitcnt lgkmcnt(3)
	v_mfma_f32_16x16x32_bf16 v[154:157], v[162:165], v[0:3], v[154:157]
	ds_read_b128 v[162:165], v94
	v_fma_f32 v39, v74, v39, -v75
	v_fma_f32 v32, v74, v32, -v75
	s_waitcnt lgkmcnt(2)
	v_mfma_f32_16x16x32_bf16 v[158:161], v[158:161], v[24:27], 0
	v_fma_f32 v33, v74, v33, -v75
	v_fma_f32 v34, v74, v34, -v75
	v_fma_f32 v35, v74, v35, -v75
	s_waitcnt lgkmcnt(1)
	v_mfma_f32_16x16x32_bf16 v[158:161], v[166:169], v[16:19], v[158:161]
	ds_read_b128 v[166:169], v96
	v_fma_f32 v44, v74, v44, -v75
	v_fma_f32 v45, v74, v45, -v75
	s_waitcnt lgkmcnt(1)
	v_mfma_f32_16x16x32_bf16 v[158:161], v[162:165], v[12:15], v[158:161]
	ds_read_b128 v[162:165], v97
	v_fma_f32 v46, v74, v46, -v75
	v_fma_f32 v47, v74, v47, -v75
	v_mfma_f32_16x16x32_bf16 v[158:161], v[170:173], v[28:31], v[158:161]
	ds_read_b128 v[170:173], v98
	v_fma_f32 v48, v74, v48, -v75
	v_fma_f32 v49, v74, v49, -v75
	s_waitcnt lgkmcnt(2)
	v_mfma_f32_16x16x32_bf16 v[158:161], v[166:169], v[20:23], v[158:161]
	ds_read_b128 v[166:169], v99
	ds_read_b128 v[174:177], v103
	s_waitcnt lgkmcnt(3)
	v_mfma_f32_16x16x32_bf16 v[158:161], v[162:165], v[8:11], v[158:161]
	ds_read_b128 v[162:165], v100
	v_fma_f32 v50, v74, v50, -v75
	v_fma_f32 v51, v74, v51, -v75
	s_waitcnt lgkmcnt(3)
	v_mfma_f32_16x16x32_bf16 v[158:161], v[170:173], v[4:7], v[158:161]
	ds_read_b128 v[170:173], v101
	v_fma_f32 v146, v74, v146, -v75
	v_fma_f32 v147, v74, v147, -v75
	s_waitcnt lgkmcnt(3)
	v_mfma_f32_16x16x32_bf16 v[166:169], v[166:169], v[0:3], v[158:161]
	v_fma_f32 v148, v74, v148, -v75
	v_fma_f32 v149, v74, v149, -v75
	v_fma_f32 v150, v74, v150, -v75
	ds_read_b128 v[158:161], v102
	s_waitcnt lgkmcnt(2)
	v_mfma_f32_16x16x32_bf16 v[162:165], v[162:165], v[24:27], 0
	v_fma_f32 v151, v74, v151, -v75
	v_fma_f32 v152, v74, v152, -v75
	v_fma_f32 v153, v74, v153, -v75
	s_waitcnt lgkmcnt(1)
	v_mfma_f32_16x16x32_bf16 v[162:165], v[170:173], v[16:19], v[162:165]
	ds_read_b128 v[170:173], v104
	v_fma_f32 v154, v74, v154, -v75
	v_fma_f32 v155, v74, v155, -v75
	s_waitcnt lgkmcnt(1)
	v_mfma_f32_16x16x32_bf16 v[158:161], v[158:161], v[12:15], v[162:165]
	v_fma_f32 v156, v74, v156, -v75
	v_fma_f32 v157, v74, v157, -v75
	v_exp_f32_e32 v142, v142
	ds_read_b128 v[162:165], v105
	v_mfma_f32_16x16x32_bf16 v[158:161], v[174:177], v[28:31], v[158:161]
	ds_read_b128 v[174:177], v106
	v_exp_f32_e32 v143, v143
	v_exp_f32_e32 v144, v144
	s_waitcnt lgkmcnt(2)
	v_mfma_f32_16x16x32_bf16 v[158:161], v[170:173], v[20:23], v[158:161]
	ds_read_b128 v[170:173], v107
	ds_read_b128 v[178:181], v140 offset:192
	s_waitcnt lgkmcnt(3)
	v_mfma_f32_16x16x32_bf16 v[158:161], v[162:165], v[8:11], v[158:161]
	ds_read_b128 v[162:165], v140
	v_exp_f32_e32 v145, v145
	v_exp_f32_e32 v40, v40
	s_waitcnt lgkmcnt(3)
	v_mfma_f32_16x16x32_bf16 v[158:161], v[174:177], v[4:7], v[158:161]
	ds_read_b128 v[174:177], v140 offset:64
	v_exp_f32_e32 v41, v41
	v_exp_f32_e32 v42, v42
	s_waitcnt lgkmcnt(3)
	v_mfma_f32_16x16x32_bf16 v[170:173], v[170:173], v[0:3], v[158:161]
	v_exp_f32_e32 v43, v43
	v_exp_f32_e32 v36, v36
	v_exp_f32_e32 v37, v37
	ds_read_b128 v[158:161], v140 offset:128
	s_waitcnt lgkmcnt(2)
	v_mfma_f32_16x16x32_bf16 v[162:165], v[162:165], v[24:27], 0
	v_exp_f32_e32 v38, v38
	v_exp_f32_e32 v39, v39
	v_exp_f32_e32 v32, v32
	s_waitcnt lgkmcnt(1)
	v_mfma_f32_16x16x32_bf16 v[162:165], v[174:177], v[16:19], v[162:165]
	ds_read_b128 v[174:177], v140 offset:256
	v_exp_f32_e32 v33, v33
	v_exp_f32_e32 v34, v34
	s_waitcnt lgkmcnt(1)
	v_mfma_f32_16x16x32_bf16 v[158:161], v[158:161], v[12:15], v[162:165]
	v_exp_f32_e32 v35, v35
	v_exp_f32_e32 v44, v44
	v_exp_f32_e32 v45, v45
	ds_read_b128 v[162:165], v140 offset:320
	v_mfma_f32_16x16x32_bf16 v[158:161], v[178:181], v[28:31], v[158:161]
	ds_read_b128 v[178:181], v140 offset:384
	v_exp_f32_e32 v46, v46
	v_exp_f32_e32 v47, v47
	s_waitcnt lgkmcnt(2)
	v_mfma_f32_16x16x32_bf16 v[158:161], v[174:177], v[20:23], v[158:161]
	ds_read_b128 v[174:177], v140 offset:448
	ds_read_b128 v[184:187], v111
	s_waitcnt lgkmcnt(3)
	v_mfma_f32_16x16x32_bf16 v[158:161], v[162:165], v[8:11], v[158:161]
	ds_read_b128 v[162:165], v108
	v_exp_f32_e32 v48, v48
	v_exp_f32_e32 v49, v49
	s_waitcnt lgkmcnt(3)
	v_mfma_f32_16x16x32_bf16 v[158:161], v[178:181], v[4:7], v[158:161]
	ds_read_b128 v[178:181], v109
	v_exp_f32_e32 v50, v50
	v_exp_f32_e32 v51, v51
	s_waitcnt lgkmcnt(3)
	v_mfma_f32_16x16x32_bf16 v[174:177], v[174:177], v[0:3], v[158:161]
	v_exp_f32_e32 v146, v146
	v_exp_f32_e32 v147, v147
	v_exp_f32_e32 v148, v148
	ds_read_b128 v[158:161], v110
	s_waitcnt lgkmcnt(2)
	v_mfma_f32_16x16x32_bf16 v[162:165], v[162:165], v[24:27], 0
	v_exp_f32_e32 v149, v149
	v_exp_f32_e32 v150, v150
	v_exp_f32_e32 v151, v151
	s_waitcnt lgkmcnt(1)
	v_mfma_f32_16x16x32_bf16 v[162:165], v[178:181], v[16:19], v[162:165]
	ds_read_b128 v[178:181], v112
	v_exp_f32_e32 v152, v152
	v_exp_f32_e32 v153, v153
	s_waitcnt lgkmcnt(1)
	v_mfma_f32_16x16x32_bf16 v[158:161], v[158:161], v[12:15], v[162:165]
	v_exp_f32_e32 v154, v154
	v_exp_f32_e32 v155, v155
	v_exp_f32_e32 v156, v156
	ds_read_b128 v[162:165], v113
	v_mfma_f32_16x16x32_bf16 v[158:161], v[184:187], v[28:31], v[158:161]
	ds_read_b128 v[184:187], v114
	v_exp_f32_e32 v157, v157
	s_addc_u32 s1, s14, s1
	s_waitcnt lgkmcnt(2)
	v_mfma_f32_16x16x32_bf16 v[158:161], v[178:181], v[20:23], v[158:161]
	ds_read_b128 v[178:181], v115
	ds_read_b128 v[188:191], v118
	ds_read_b128 v[192:195], v119
	s_waitcnt lgkmcnt(4)
	v_mfma_f32_16x16x32_bf16 v[158:161], v[162:165], v[8:11], v[158:161]
	ds_read_b128 v[162:165], v116
	ds_read_b128 v[196:199], v121
	s_waitcnt lgkmcnt(5)
	v_mfma_f32_16x16x32_bf16 v[158:161], v[184:187], v[4:7], v[158:161]
	ds_read_b128 v[184:187], v117
	s_waitcnt lgkmcnt(2)
	v_mfma_f32_16x16x32_bf16 v[162:165], v[162:165], v[24:27], 0
	v_mfma_f32_16x16x32_bf16 v[178:181], v[178:181], v[0:3], v[158:161]
	s_nop 3
	v_fma_f32 v158, v74, v166, -v75
	v_exp_f32_e32 v159, v158
	v_fma_f32 v158, v74, v167, -v75
	s_waitcnt lgkmcnt(0)
	v_mfma_f32_16x16x32_bf16 v[164:167], v[184:187], v[16:19], v[162:165]
	ds_read_b128 v[184:187], v120
	v_exp_f32_e32 v161, v158
	v_fma_f32 v158, v74, v168, -v75
	v_mfma_f32_16x16x32_bf16 v[188:191], v[188:191], v[12:15], v[164:167]
	v_exp_f32_e32 v163, v158
	v_fma_f32 v158, v74, v169, -v75
	v_fma_f32 v160, v74, v173, -v75
	v_mfma_f32_16x16x32_bf16 v[188:191], v[192:195], v[28:31], v[188:191]
	ds_read_b128 v[192:195], v122
	v_exp_f32_e32 v165, v158
	v_fma_f32 v158, v74, v170, -v75
	s_waitcnt lgkmcnt(1)
	v_mfma_f32_16x16x32_bf16 v[184:187], v[184:187], v[20:23], v[188:191]
	v_exp_f32_e32 v166, v158
	v_fma_f32 v158, v74, v171, -v75
	v_exp_f32_e32 v168, v158
	ds_read_b128 v[188:191], v123
	v_mfma_f32_16x16x32_bf16 v[184:187], v[196:199], v[8:11], v[184:187]
	ds_read_b128 v[196:199], v124
	v_fma_f32 v158, v74, v172, -v75
	ds_read_b128 v[170:173], v125
	s_waitcnt lgkmcnt(3)
	v_mfma_f32_16x16x32_bf16 v[184:187], v[192:195], v[4:7], v[184:187]
	v_fma_f32 v162, v74, v174, -v75
	v_fma_f32 v164, v74, v175, -v75
	v_fma_f32 v167, v74, v176, -v75
	s_waitcnt lgkmcnt(2)
	v_mfma_f32_16x16x32_bf16 v[184:187], v[188:191], v[0:3], v[184:187]
	ds_read_b128 v[188:191], v126
	v_fma_f32 v169, v74, v177, -v75
	ds_read_b128 v[174:177], v129
	s_waitcnt lgkmcnt(3)
	v_mfma_f32_16x16x32_bf16 v[192:195], v[196:199], v[24:27], 0
	ds_read_b128 v[196:199], v127
	v_fma_f32 v178, v74, v178, -v75
	v_exp_f32_e32 v158, v158
	s_waitcnt lgkmcnt(3)
	v_mfma_f32_16x16x32_bf16 v[170:173], v[170:173], v[16:19], v[192:195]
	v_exp_f32_e32 v160, v160
	v_exp_f32_e32 v162, v162
	v_exp_f32_e32 v164, v164
	ds_read_b128 v[192:195], v128
	s_waitcnt lgkmcnt(3)
	v_mfma_f32_16x16x32_bf16 v[170:173], v[188:191], v[12:15], v[170:173]
	ds_read_b128 v[188:191], v130
	v_exp_f32_e32 v167, v167
	v_exp_f32_e32 v169, v169
	s_waitcnt lgkmcnt(2)
	v_mfma_f32_16x16x32_bf16 v[170:173], v[196:199], v[28:31], v[170:173]
	ds_read_b128 v[196:199], v131
	s_waitcnt lgkmcnt(2)
	v_mfma_f32_16x16x32_bf16 v[192:195], v[192:195], v[20:23], v[170:173]
	v_mfma_f32_16x16x32_bf16 v[172:175], v[174:177], v[8:11], v[192:195]
	s_nop 3
	v_exp_f32_e32 v170, v178
	v_fma_f32 v171, v74, v179, -v75
	ds_read_b128 v[176:179], v141
	ds_read_b128 v[192:195], v141 offset:64
	s_waitcnt lgkmcnt(3)
	v_mfma_f32_16x16x32_bf16 v[188:191], v[188:191], v[4:7], v[172:175]
	v_exp_f32_e32 v171, v171
	s_waitcnt lgkmcnt(2)
	v_mfma_f32_16x16x32_bf16 v[188:191], v[196:199], v[0:3], v[188:191]
	ds_read_b128 v[196:199], v141 offset:128
	v_fma_f32 v172, v74, v180, -v75
	v_fma_f32 v173, v74, v181, -v75
	s_waitcnt lgkmcnt(2)
	v_mfma_f32_16x16x32_bf16 v[174:177], v[176:179], v[24:27], 0
	ds_read_b128 v[178:181], v141 offset:192
	v_fma_f32 v24, v74, v184, -v75
	v_exp_f32_e32 v26, v24
	s_waitcnt lgkmcnt(2)
	v_mfma_f32_16x16x32_bf16 v[16:19], v[192:195], v[16:19], v[174:177]
	ds_read_b128 v[192:195], v141 offset:256
	v_fma_f32 v24, v74, v185, -v75
	v_exp_f32_e32 v27, v24
	s_waitcnt lgkmcnt(2)
	v_mfma_f32_16x16x32_bf16 v[12:15], v[196:199], v[12:15], v[16:19]
	v_fma_f32 v24, v74, v187, -v75
	v_exp_f32_e32 v172, v172
	v_exp_f32_e32 v173, v173
	v_fma_f32 v16, v74, v186, -v75
	v_exp_f32_e32 v174, v16
	ds_read_b128 v[16:19], v141 offset:320
	s_waitcnt lgkmcnt(2)
	v_mfma_f32_16x16x32_bf16 v[12:15], v[178:181], v[28:31], v[12:15]
	ds_read_b128 v[176:179], v141 offset:384
	v_exp_f32_e32 v28, v24
	s_waitcnt lgkmcnt(2)
	v_mfma_f32_16x16x32_bf16 v[12:15], v[192:195], v[20:23], v[12:15]
	v_fma_f32 v20, v74, v188, -v75
	v_exp_f32_e32 v29, v20
	ds_read_b128 v[20:23], v141 offset:448
	s_waitcnt lgkmcnt(2)
	v_mfma_f32_16x16x32_bf16 v[8:11], v[16:19], v[8:11], v[12:15]
	s_waitcnt lgkmcnt(0)
	s_barrier
	v_mfma_f32_16x16x32_bf16 v[4:7], v[176:179], v[4:7], v[8:11]
	v_fma_f32 v12, v74, v189, -v75
	v_exp_f32_e32 v31, v12
	v_fma_f32 v12, v74, v190, -v75
	v_mfma_f32_16x16x32_bf16 v[0:3], v[20:23], v[0:3], v[4:7]
	s_nop 0
	v_fma_f32 v8, v74, v191, -v75
	v_exp_f32_e32 v30, v12
	v_exp_f32_e32 v175, v8
	v_lshl_add_u64 v[10:11], v[68:69], 0, s[0:1]
	s_nop 0
	s_nop 1
	v_fma_f32 v0, v74, v0, -v75
	v_exp_f32_e32 v176, v0
	v_fma_f32 v0, v74, v1, -v75
	v_exp_f32_e32 v177, v0
	v_fma_f32 v0, v74, v2, -v75
	v_exp_f32_e32 v178, v0
	v_fma_f32 v0, v74, v3, -v75
	v_exp_f32_e32 v74, v0
	v_lshl_add_u64 v[12:13], v[64:65], 0, s[0:1]
	v_lshl_add_u64 v[14:15], v[66:67], 0, s[0:1]
	v_add_co_u32_e32 v16, vcc, 0x19800000, v10
	s_mov_b32 s1, 0
	s_mov_b32 s0, 0x28000
	v_addc_co_u32_e32 v17, vcc, 0, v11, vcc
	global_load_dwordx4 v[184:187], v[16:17], off
	global_load_dwordx4 v[188:191], v[14:15], off
	v_lshl_add_u64 v[18:19], v[16:17], 0, s[0:1]
	global_load_dwordx4 v[192:195], v[18:19], off
	global_load_dwordx4 v[196:199], v[12:13], off
	s_mov_b32 s0, 0x50000
	v_lshl_add_u64 v[18:19], v[16:17], 0, s[0:1]
	global_load_dwordx4 v[200:203], v[18:19], off
	v_lshl_add_u64 v[20:21], v[14:15], 0, s[0:1]
	global_load_dwordx4 v[204:207], v[20:21], off
	v_lshl_add_u64 v[22:23], v[12:13], 0, s[0:1]
	global_load_dwordx4 v[212:215], v[22:23], off
	s_mov_b32 s0, 0x78000
	v_lshl_add_u64 v[18:19], v[16:17], 0, s[0:1]
	global_load_dwordx4 v[208:211], v[18:19], off
	s_mov_b32 s0, 0xa0000
	v_lshl_add_u64 v[18:19], v[16:17], 0, s[0:1]
	global_load_dwordx4 v[216:219], v[18:19], off
	v_lshl_add_u64 v[20:21], v[14:15], 0, s[0:1]
	global_load_dwordx4 v[220:223], v[20:21], off
	v_lshl_add_u64 v[22:23], v[12:13], 0, s[0:1]
	global_load_dwordx4 v[228:231], v[22:23], off
	s_mov_b32 s0, 0xc8000
	v_lshl_add_u64 v[18:19], v[16:17], 0, s[0:1]
	global_load_dwordx4 v[224:227], v[18:19], off
	s_mov_b32 s0, 0xf0000
	v_lshl_add_u64 v[18:19], v[16:17], 0, s[0:1]
	global_load_dwordx4 v[232:235], v[18:19], off
	v_lshl_add_u64 v[20:21], v[14:15], 0, s[0:1]
	global_load_dwordx4 v[236:239], v[20:21], off
	v_lshl_add_u64 v[22:23], v[12:13], 0, s[0:1]
	global_load_dwordx4 v[246:249], v[22:23], off
	s_mov_b32 s0, 0x118000
	v_lshl_add_u64 v[18:19], v[16:17], 0, s[0:1]
	global_load_dwordx4 v[240:243], v[18:19], off
	v_add_f32_e32 v21, 0, v142
	v_add_f32_e32 v21, v143, v21
	v_add_f32_e32 v21, v144, v21
	v_add_f32_e32 v21, v145, v21
	v_add_f32_e32 v21, v21, v40
	v_add_f32_e32 v21, v41, v21
	v_add_f32_e32 v21, v42, v21
	v_add_f32_e32 v21, v43, v21
	v_add_f32_e32 v21, v21, v36
	v_add_f32_e32 v21, v37, v21
	v_add_f32_e32 v21, v38, v21
	v_add_f32_e32 v21, v39, v21
	v_add_f32_e32 v21, v21, v32
	v_add_f32_e32 v21, v33, v21
	v_add_f32_e32 v21, v34, v21
	v_add_f32_e32 v21, v35, v21
	v_add_f32_e32 v21, v21, v44
	v_add_f32_e32 v21, v45, v21
	v_add_f32_e32 v21, v46, v21
	v_add_f32_e32 v21, v47, v21
	v_add_f32_e32 v21, v21, v48
	v_add_f32_e32 v21, v49, v21
	v_add_f32_e32 v21, v50, v21
	v_add_f32_e32 v21, v51, v21
	v_add_f32_e32 v21, v21, v146
	v_add_f32_e32 v21, v147, v21
	v_add_f32_e32 v21, v148, v21
	v_add_f32_e32 v21, v149, v21
	v_add_f32_e32 v21, v21, v150
	v_add_f32_e32 v21, v151, v21
	v_add_f32_e32 v21, v152, v21
	v_add_f32_e32 v21, v153, v21
	v_add_f32_e32 v21, v21, v154
	v_add_f32_e32 v21, v155, v21
	v_add_f32_e32 v21, v156, v21
	v_add_f32_e32 v21, v157, v21
	v_add_f32_e32 v21, v21, v159
	v_add_f32_e32 v21, v161, v21
	v_add_f32_e32 v21, v163, v21
	v_add_f32_e32 v21, v165, v21
	v_add_f32_e32 v21, v21, v166
	v_add_f32_e32 v21, v168, v21
	v_add_f32_e32 v21, v158, v21
	v_add_f32_e32 v21, v160, v21
	v_add_f32_e32 v21, v21, v162
	v_add_f32_e32 v21, v164, v21
	v_add_f32_e32 v21, v167, v21
	v_add_f32_e32 v21, v169, v21
	v_add_f32_e32 v21, v21, v170
	v_add_f32_e32 v21, v171, v21
	v_add_f32_e32 v21, v172, v21
	v_add_f32_e32 v21, v173, v21
	v_add_f32_e32 v21, v21, v26
	v_add_f32_e32 v21, v27, v21
	v_add_f32_e32 v21, v174, v21
	v_add_f32_e32 v21, v28, v21
	v_add_f32_e32 v21, v21, v29
	v_add_f32_e32 v21, v31, v21
	v_add_f32_e32 v21, v30, v21
	v_add_f32_e32 v21, v175, v21
	v_add_f32_e32 v21, v21, v176
	v_add_f32_e32 v21, v177, v21
	v_add_f32_e32 v21, v178, v21
	v_add_f32_e32 v25, v74, v21
	v_cvt_pk_bf16_f32 v6, v32, v33
	ds_bpermute_b32 v32, v80, v25
	v_cvt_pk_bf16_f32 v7, v34, v35
	v_cvt_pk_bf16_f32 v4, v36, v37
	s_waitcnt lgkmcnt(0)
	v_cvt_pk_bf16_f32 v0, v142, v143
	s_waitcnt lgkmcnt(0)
	v_add_f32_e32 v32, v25, v32
	ds_bpermute_b32 v33, v81, v32
	v_cvt_pk_bf16_f32 v1, v144, v145
	v_cvt_pk_bf16_f32 v2, v40, v41
	v_cvt_pk_bf16_f32 v3, v42, v43
	v_cvt_pk_bf16_f32 v5, v38, v39
	s_waitcnt lgkmcnt(0)
	v_add_f32_e32 v32, v32, v33
	v_div_scale_f32 v33, s[0:1], v32, v32, 1.0
	v_rcp_f32_e32 v34, v33
	v_cvt_pk_bf16_f32 v8, v44, v45
	v_cvt_pk_bf16_f32 v9, v46, v47
	v_cvt_pk_bf16_f32 v10, v48, v49
	v_fma_f32 v35, -v33, v34, 1.0
	v_fmac_f32_e32 v34, v35, v34
	v_div_scale_f32 v35, vcc, 1.0, v32, 1.0
	v_mul_f32_e32 v36, v35, v34
	v_fma_f32 v37, -v33, v36, v35
	v_fmac_f32_e32 v36, v37, v34
	v_fma_f32 v33, -v33, v36, v35
	v_div_fmas_f32 v33, v33, v34, v36
	v_div_fixup_f32 v32, v33, v32, 1.0
	v_lshl_add_u64 v[34:35], v[72:73], 0, s[10:11]
	v_cvt_pk_bf16_f32 v11, v50, v51
	v_cvt_pk_bf16_f32 v12, v146, v147
	v_cvt_pk_bf16_f32 v13, v148, v149
	v_cvt_pk_bf16_f32 v14, v150, v151
	v_cvt_pk_bf16_f32 v15, v152, v153
	v_cvt_pk_bf16_f32 v16, v154, v155
	v_cvt_pk_bf16_f32 v17, v156, v157
	v_cvt_pk_bf16_f32 v18, v159, v161
	v_cvt_pk_bf16_f32 v19, v163, v165
	v_cvt_pk_bf16_f32 v20, v166, v168
	v_cvt_pk_bf16_f32 v21, v158, v160
	v_cvt_pk_bf16_f32 v22, v162, v164
	v_cvt_pk_bf16_f32 v23, v167, v169
	v_cvt_pk_bf16_f32 v24, v170, v171
	v_cvt_pk_bf16_f32 v25, v172, v173
	v_cvt_pk_bf16_f32 v26, v26, v27
	v_cvt_pk_bf16_f32 v27, v174, v28
	v_cvt_pk_bf16_f32 v28, v29, v31
	v_cvt_pk_bf16_f32 v29, v30, v175
	v_cvt_pk_bf16_f32 v30, v176, v177
	v_cvt_pk_bf16_f32 v31, v178, v74
	v_mov_b32_e32 v33, v32
	v_lshl_add_u64 v[34:35], v[70:71], 0, v[34:35]
	v_mov_b32_e32 v44, v134
	v_mov_b32_e32 v45, v133
	v_mov_b32_e32 v46, v132
	s_waitcnt vmcnt(12)
	ds_write_b128 v44, v[184:187]
	ds_write_b128 v45, v[188:191]
	ds_write_b128 v44, v[192:195] offset:16896
	ds_write_b128 v46, v[196:199]
	v_add_u32_e32 v44, 0x8400, v44
	v_add_u32_e32 v45, 0x8400, v45
	v_add_u32_e32 v46, 0x8400, v46
	s_waitcnt vmcnt(8)
	ds_write_b128 v44, v[200:203]
	ds_write_b128 v45, v[204:207]
	ds_write_b128 v44, v[208:211] offset:16896
	ds_write_b128 v46, v[212:215]
	v_add_u32_e32 v44, 0x8400, v44
	v_add_u32_e32 v45, 0x8400, v45
	v_add_u32_e32 v46, 0x8400, v46
	s_waitcnt vmcnt(4)
	ds_write_b128 v44, v[216:219]
	ds_write_b128 v45, v[220:223]
	ds_write_b128 v44, v[224:227] offset:16896
	ds_write_b128 v46, v[228:231]
	v_add_u32_e32 v44, 0x8400, v44
	v_add_u32_e32 v45, 0x8400, v45
	v_add_u32_e32 v46, 0x8400, v46
	s_waitcnt vmcnt(0)
	ds_write_b128 v44, v[232:235]
	ds_write_b128 v45, v[236:239]
	ds_write_b128 v44, v[240:243] offset:16896
	ds_write_b128 v46, v[246:249]
	s_waitcnt lgkmcnt(0)
	s_mov_b32 s0, 0
	s_barrier
	v_add_u32_e32 v48, s0, v135
	v_add_u32_e32 v49, 0x4200, v135
	ds_read_b64 v[142:143], v48 offset:0
	ds_read_b64 v[144:145], v48 offset:32
	ds_read_b64 v[146:147], v48 offset:8448
	ds_read_b64 v[148:149], v48 offset:8480
	ds_read_b64 v[150:151], v48 offset:64
	ds_read_b64 v[152:153], v48 offset:96
	ds_read_b64 v[154:155], v48 offset:8512
	ds_read_b64 v[156:157], v48 offset:8544
	ds_read_b64 v[158:159], v48 offset:128
	ds_read_b64 v[160:161], v48 offset:160
	ds_read_b64 v[162:163], v48 offset:8576
	ds_read_b64 v[164:165], v48 offset:8608
.LBB0_1954:
	ds_read_b64 v[166:167], v48 offset:192
	ds_read_b64 v[168:169], v48 offset:224
	s_waitcnt lgkmcnt(12)
	v_mfma_f32_16x16x32_bf16 v[36:39], v[142:145], v[0:3], 0
	ds_read_b64 v[170:171], v48 offset:8640
	ds_read_b64 v[172:173], v48 offset:8672
	s_waitcnt lgkmcnt(12)
	v_mfma_f32_16x16x32_bf16 v[40:43], v[146:149], v[0:3], 0
	ds_read_b64 v[142:143], v48 offset:256
	ds_read_b64 v[144:145], v48 offset:288
	s_waitcnt lgkmcnt(12)
	v_mfma_f32_16x16x32_bf16 v[36:39], v[150:153], v[4:7], v[36:39]
	ds_read_b64 v[146:147], v48 offset:8704
	ds_read_b64 v[148:149], v48 offset:8736
	s_waitcnt lgkmcnt(12)
	v_mfma_f32_16x16x32_bf16 v[40:43], v[154:157], v[4:7], v[40:43]
	ds_read_b64 v[150:151], v48 offset:320
	ds_read_b64 v[152:153], v48 offset:352
	s_waitcnt lgkmcnt(12)
	v_mfma_f32_16x16x32_bf16 v[36:39], v[158:161], v[8:11], v[36:39]
	ds_read_b64 v[154:155], v48 offset:8768
	ds_read_b64 v[156:157], v48 offset:8800
	s_waitcnt lgkmcnt(12)
	v_mfma_f32_16x16x32_bf16 v[40:43], v[162:165], v[8:11], v[40:43]
	ds_read_b64 v[158:159], v48 offset:384
	ds_read_b64 v[160:161], v48 offset:416
	s_waitcnt lgkmcnt(12)
	v_mfma_f32_16x16x32_bf16 v[36:39], v[166:169], v[12:15], v[36:39]
	ds_read_b64 v[162:163], v48 offset:8832
	ds_read_b64 v[164:165], v48 offset:8864
	s_waitcnt lgkmcnt(12)
	v_mfma_f32_16x16x32_bf16 v[40:43], v[170:173], v[12:15], v[40:43]
	ds_read_b64 v[166:167], v48 offset:448
	ds_read_b64 v[168:169], v48 offset:480
	s_waitcnt lgkmcnt(12)
	v_mfma_f32_16x16x32_bf16 v[36:39], v[142:145], v[16:19], v[36:39]
	ds_read_b64 v[170:171], v48 offset:8896
	ds_read_b64 v[172:173], v48 offset:8928
	s_waitcnt lgkmcnt(12)
	v_mfma_f32_16x16x32_bf16 v[40:43], v[146:149], v[16:19], v[40:43]
	ds_read_b64 v[142:143], v49 offset:0
	ds_read_b64 v[144:145], v49 offset:32
	s_waitcnt lgkmcnt(12)
	v_mfma_f32_16x16x32_bf16 v[36:39], v[150:153], v[20:23], v[36:39]
	ds_read_b64 v[146:147], v49 offset:8448
	ds_read_b64 v[148:149], v49 offset:8480
	s_waitcnt lgkmcnt(12)
	v_mfma_f32_16x16x32_bf16 v[40:43], v[154:157], v[20:23], v[40:43]
	ds_read_b64 v[150:151], v49 offset:64
	ds_read_b64 v[152:153], v49 offset:96
	s_waitcnt lgkmcnt(12)
	v_mfma_f32_16x16x32_bf16 v[36:39], v[158:161], v[24:27], v[36:39]
	ds_read_b64 v[154:155], v49 offset:8512
	ds_read_b64 v[156:157], v49 offset:8544
	s_waitcnt lgkmcnt(12)
	v_mfma_f32_16x16x32_bf16 v[40:43], v[162:165], v[24:27], v[40:43]
	ds_read_b64 v[158:159], v49 offset:128
	ds_read_b64 v[160:161], v49 offset:160
	s_waitcnt lgkmcnt(12)
	v_mfma_f32_16x16x32_bf16 v[36:39], v[166:169], v[28:31], v[36:39]
	ds_read_b64 v[162:163], v49 offset:8576
	ds_read_b64 v[164:165], v49 offset:8608
	s_waitcnt lgkmcnt(12)
	v_mfma_f32_16x16x32_bf16 v[40:43], v[170:173], v[28:31], v[40:43]
	s_addk_i32 s0, 0x4200
	s_add_i32 s1, s0, 0x4200
	s_cmp_lg_u32 s1, 0x21000
	s_cselect_b32 s1, s1, 0
	s_cmp_lg_u32 s0, 0x21000
	s_nop 2
	v_pk_mul_f32 v[36:37], v[32:33], v[36:37]
	v_pk_mul_f32 v[38:39], v[32:33], v[38:39]
	v_pk_mul_f32 v[40:41], v[32:33], v[40:41]
	v_pk_mul_f32 v[42:43], v[32:33], v[42:43]
	v_cvt_pk_bf16_f32 v36, v36, v37
	v_cvt_pk_bf16_f32 v37, v38, v39
	v_cvt_pk_bf16_f32 v38, v40, v41
	v_cvt_pk_bf16_f32 v39, v42, v43
	global_store_dwordx2 v[34:35], v[36:37], off offset:-32
	global_store_dwordx2 v[34:35], v[38:39], off
	v_lshl_add_u64 v[34:35], v[34:35], 0, 64
	v_add_u32_e32 v48, s0, v135
	v_add_u32_e32 v49, s1, v135
	s_cbranch_scc1 .LBB0_1954
	s_waitcnt lgkmcnt(0)
	s_add_i32 s69, s69, s86
	s_cmpk_lt_i32 s69, 0x600
	s_barrier
	s_cbranch_scc1 .LBB0_1949

	.amdhsa_kernel _Z9hymba_fwd4Args
		.amdhsa_group_segment_fixed_size 0
		.amdhsa_private_segment_fixed_size 0
		.amdhsa_kernarg_size 496
		.amdhsa_user_sgpr_count 2
		.amdhsa_user_sgpr_dispatch_ptr 0
		.amdhsa_user_sgpr_queue_ptr 0
		.amdhsa_user_sgpr_kernarg_segment_ptr 1
		.amdhsa_user_sgpr_dispatch_id 0
		.amdhsa_user_sgpr_kernarg_preload_length 0
		.amdhsa_user_sgpr_kernarg_preload_offset 0
		.amdhsa_user_sgpr_private_segment_size 0
		.amdhsa_uses_dynamic_stack 0
		.amdhsa_enable_private_segment 0
		.amdhsa_system_sgpr_workgroup_id_x 1
		.amdhsa_system_sgpr_workgroup_id_y 0
		.amdhsa_system_sgpr_workgroup_id_z 0
		.amdhsa_system_sgpr_workgroup_info 0
		.amdhsa_system_vgpr_workitem_id 2
		.amdhsa_next_free_vgpr 256
		.amdhsa_next_free_sgpr 98
		.amdhsa_accum_offset 256
		.amdhsa_reserve_vcc 1
		.amdhsa_float_round_mode_32 0
		.amdhsa_float_round_mode_16_64 0
		.amdhsa_float_denorm_mode_32 3
		.amdhsa_float_denorm_mode_16_64 3
		.amdhsa_dx10_clamp 1
		.amdhsa_ieee_mode 1
		.amdhsa_fp16_overflow 0
		.amdhsa_tg_split 0
		.amdhsa_exception_fp_ieee_invalid_op 0
		.amdhsa_exception_fp_denorm_src 0
		.amdhsa_exception_fp_ieee_div_zero 0
		.amdhsa_exception_fp_ieee_overflow 0
		.amdhsa_exception_fp_ieee_underflow 0
		.amdhsa_exception_fp_ieee_inexact 0
		.amdhsa_exception_int_div_zero 0
	.end_amdhsa_kernel

amdhsa.kernels:
  - .agpr_count:     0
    .args:
      - .offset:         0
        .size:           240
        .value_kind:     by_value
      - .offset:         240
        .size:           4
        .value_kind:     hidden_block_count_x
      - .offset:         244
        .size:           4
        .value_kind:     hidden_block_count_y
      - .offset:         248
        .size:           4
        .value_kind:     hidden_block_count_z
      - .offset:         252
        .size:           2
        .value_kind:     hidden_group_size_x
      - .offset:         254
        .size:           2
        .value_kind:     hidden_group_size_y
      - .offset:         256
        .size:           2
        .value_kind:     hidden_group_size_z
      - .offset:         258
        .size:           2
        .value_kind:     hidden_remainder_x
      - .offset:         260
        .size:           2
        .value_kind:     hidden_remainder_y
      - .offset:         262
        .size:           2
        .value_kind:     hidden_remainder_z
      - .offset:         280
        .size:           8
        .value_kind:     hidden_global_offset_x
      - .offset:         288
        .size:           8
        .value_kind:     hidden_global_offset_y
      - .offset:         296
        .size:           8
        .value_kind:     hidden_global_offset_z
      - .offset:         304
        .size:           2
        .value_kind:     hidden_grid_dims
      - .offset:         328
        .size:           8
        .value_kind:     hidden_multigrid_sync_arg
      - .offset:         360
        .size:           4
        .value_kind:     hidden_dynamic_lds_size
    .group_segment_fixed_size: 0
    .kernarg_segment_align: 8
    .kernarg_segment_size: 496
    .language:       OpenCL C
    .language_version:
      - 2
      - 0
    .max_flat_workgroup_size: 512
    .name:           _Z9hymba_fwd4Args
    .private_segment_fixed_size: 0
    .sgpr_count:     104
    .sgpr_spill_count: 264
    .symbol:         _Z9hymba_fwd4Args.kd
    .uniform_work_group_size: 1
    .uses_dynamic_stack: false
    .vgpr_count:     256
    .vgpr_spill_count: 0
    .wavefront_size: 64
